# v32 + prep: drop the full vmcnt drain at the ten tr_cvt call boundaries (only stores outstanding there) so the next call's first loads overlap the store drain
# baseline (speedup 1.0000x reference)
; __device__ __forceinline__ const float* INP(const Params& p, int i) { asm volatile("" : "+s"(i)); return p.in[i]; }
; __device__ __forceinline__ int BID() { int t = blockIdx.x; asm volatile("" : "+s"(t)); return t; }
; __device__ __forceinline__ int NBLK() { int t = gridDim.x; asm volatile("" : "+s"(t)); return t; }
; __device__ __forceinline__ void tr_cvt(const float* __restrict__ src, const float* __restrict__ src2, int srcsel, int ld, int K, int N, bf16_t* __restrict__ dst, LAS float* tl) {
;     ...
;     const int G2 = 2 * NBLK();
;     int t = BID();
;     if (t < ntiles) TRC_LOAD(t, 0);
;     if (t + NBLK() < ntiles) TRC_LOAD(t + NBLK(), 1);
; __device__ void prep_phase(const Params& p, int l, LAS unsigned char* lds) {
;     ...
;     tr_cvt(INP(p, 4) + (size_t)l * FF_ * D_, nullptr, 0, D_, FF_, D_, W + W_D1, tl);
.LBB0_763:
	s_mov_b32 s10, 4
	s_ashr_i32 s11, s10, 31
	s_lshl_b64 s[10:11], s[10:11], 3
	s_add_u32 s10, s0, s10
	s_addc_u32 s11, s1, s11
	s_load_dwordx2 s[10:11], s[10:11], 0x0
	v_mov_b32_e32 v25, v168
	s_mov_b32 s14, s39
	v_lshlrev_b32_e32 v0, 2, v25
	s_waitcnt lgkmcnt(0)
	s_add_u32 s10, s10, s6
	s_addc_u32 s11, s11, s7
	s_mov_b32 s18, s73
	v_and_b32_e32 v20, 60, v0
	s_cmpk_lt_i32 s18, 0x2c0
	v_ashrrev_i32_e32 v24, 4, v25
	s_cselect_b64 s[12:13], -1, 0
	s_cmpk_gt_i32 s18, 0x2bf
	v_lshlrev_b32_e32 v22, 2, v20
	s_cbranch_scc1 .LBB0_765
	s_mul_hi_i32 s15, s18, 0x2e8ba2e9
	s_lshr_b32 s16, s15, 31
	s_ashr_i32 s15, s15, 3
	s_add_i32 s15, s15, s16
	s_mul_i32 s16, s15, 44
	s_sub_i32 s17, s18, s16
	v_lshl_add_u32 v2, s17, 6, v24
	v_ashrrev_i32_e32 v3, 31, v2
	s_lshl_b32 s16, s15, 6
	v_lshlrev_b64 v[2:3], 12, v[2:3]
	v_lshl_add_u64 v[2:3], s[10:11], 0, v[2:3]
	s_ashr_i32 s17, s16, 31
	v_lshl_add_u64 v[2:3], s[16:17], 2, v[2:3]
	v_mov_b32_e32 v23, v1
	v_lshl_add_u64 v[2:3], v[2:3], 0, v[22:23]
	v_add_co_u32_e32 v8, vcc, 0x20000, v2
	s_nop 1
	v_addc_co_u32_e32 v9, vcc, 0, v3, vcc
	global_load_dwordx4 v[4:7], v[2:3], off
	s_nop 0
	global_load_dwordx4 v[8:11], v[8:9], off
	s_branch .LBB0_766
.LBB0_765:
	v_mov_b32_e32 v2, v1
	v_mov_b32_e32 v3, v1
	v_mov_b32_e32 v0, v1
	v_mov_b64_e32 v[6:7], v[2:3]
	v_mov_b64_e32 v[10:11], v[2:3]
	v_mov_b64_e32 v[4:5], v[0:1]
	v_mov_b64_e32 v[8:9], v[0:1]
.LBB0_766:
	s_mov_b32 s15, s39
	s_add_i32 s15, s15, s18
	s_cmpk_gt_i32 s15, 0x2bf
	s_cbranch_scc1 .LBB0_768
	s_mov_b32 s15, s39
	s_add_i32 s15, s15, s18
	s_mul_hi_i32 s16, s15, 0x2e8ba2e9
	s_lshr_b32 s17, s16, 31
	s_lshr_b32 s16, s16, 3
	s_add_i32 s16, s16, s17
	s_mul_i32 s16, s16, 44
	s_sub_i32 s15, s15, s16
	s_mov_b32 s16, s39
	s_add_i32 s16, s16, s18
	s_mul_hi_i32 s16, s16, 0x2e8ba2e9
	s_lshr_b32 s17, s16, 31
	s_lshr_b32 s16, s16, 3
	v_lshl_add_u32 v2, s15, 6, v24
	s_add_i32 s16, s16, s17
	v_ashrrev_i32_e32 v3, 31, v2
	s_lshl_b32 s16, s16, 6
	v_lshlrev_b64 v[2:3], 12, v[2:3]
	v_lshl_add_u64 v[2:3], s[10:11], 0, v[2:3]
	s_ashr_i32 s17, s16, 31
	v_lshl_add_u64 v[2:3], s[16:17], 2, v[2:3]
	v_mov_b32_e32 v23, v1
	v_lshl_add_u64 v[2:3], v[2:3], 0, v[22:23]
	v_add_co_u32_e32 v16, vcc, 0x20000, v2
	s_nop 1
	v_addc_co_u32_e32 v17, vcc, 0, v3, vcc
	global_load_dwordx4 v[12:15], v[2:3], off
	s_nop 0
	global_load_dwordx4 v[16:19], v[16:17], off
	s_andn2_b64 vcc, exec, s[12:13]
	s_cbranch_vccz .LBB0_769
	s_branch .LBB0_779

; __device__ __forceinline__ int BID() { int t = blockIdx.x; asm volatile("" : "+s"(t)); return t; }
; __device__ __forceinline__ int NBLK() { int t = gridDim.x; asm volatile("" : "+s"(t)); return t; }
; __device__ __forceinline__ void tr_cvt(const float* __restrict__ src, const float* __restrict__ src2, int srcsel, int ld, int K, int N, bf16_t* __restrict__ dst, LAS float* tl) {
;     ...
;     const int G2 = 2 * NBLK();
;     int t = BID();
;     if (t < ntiles) TRC_LOAD(t, 0);
;     if (t + NBLK() < ntiles) TRC_LOAD(t + NBLK(), 1);
; __device__ void prep_phase(const Params& p, int l, LAS unsigned char* lds) {
;     ...
;     tr_cvt(w_in, nullptr, 0, WINC, D_, 1536, W + W_IN, tl);
.LBB0_779:
	v_readlane_b32 s10, v254, 31
	v_readlane_b32 s11, v254, 32
	s_mov_b32 s12, s10
	s_ashr_i32 s13, s10, 31
	s_mul_i32 s11, s12, 0x1b00000
	s_mul_hi_i32 s10, s10, 0x1b00000
	s_add_u32 s8, s8, s11
	v_mov_b32_e32 v25, v168
	s_addc_u32 s9, s9, s10
	s_mov_b32 s14, s39
	v_lshlrev_b32_e32 v0, 2, v25
	s_mov_b32 s16, s73
	v_and_b32_e32 v20, 60, v0
	s_cmpk_lt_i32 s16, 0x180
	s_mov_b64 s[60:61], s[12:13]
	v_ashrrev_i32_e32 v24, 4, v25
	s_cselect_b64 s[12:13], -1, 0
	s_cmpk_gt_i32 s16, 0x17f
	v_lshlrev_b32_e32 v22, 2, v20
	s_cbranch_scc1 .LBB0_781
	s_ashr_i32 s10, s16, 31
	s_lshr_b32 s10, s10, 28
	s_add_i32 s10, s16, s10
	s_and_b32 s11, s10, 0x3fffff0
	s_lshl_b32 s10, s10, 2
	s_sub_i32 s11, s16, s11
	s_andn2_b32 s10, s10, 63
	v_lshl_add_u32 v0, s11, 6, v24
	v_mov_b64_e32 v[2:3], s[8:9]
	s_ashr_i32 s11, s10, 31
	v_mad_i64_i32 v[4:5], s[18:19], v0, s69, v[2:3]
	s_lshl_b64 s[10:11], s[10:11], 2
	v_add_u32_e32 v0, 32, v0
	v_lshl_add_u64 v[4:5], v[4:5], 0, s[10:11]
	v_mov_b32_e32 v23, v1
	v_mad_i64_i32 v[2:3], s[18:19], v0, s69, v[2:3]
	v_lshl_add_u64 v[4:5], v[4:5], 0, v[22:23]
	v_lshl_add_u64 v[2:3], v[2:3], 0, s[10:11]
	v_lshl_add_u64 v[2:3], v[2:3], 0, v[22:23]
	global_load_dwordx4 v[4:7], v[4:5], off
	s_nop 0
	global_load_dwordx4 v[8:11], v[2:3], off
	s_branch .LBB0_782
.LBB0_781:
	v_mov_b32_e32 v2, v1
	v_mov_b32_e32 v3, v1
	v_mov_b32_e32 v0, v1
	v_mov_b64_e32 v[6:7], v[2:3]
	v_mov_b64_e32 v[10:11], v[2:3]
	v_mov_b64_e32 v[4:5], v[0:1]
	v_mov_b64_e32 v[8:9], v[0:1]
.LBB0_782:
	s_mov_b32 s10, s39
	s_add_i32 s10, s10, s16
	s_cmpk_gt_i32 s10, 0x17f
	s_cbranch_scc1 .LBB0_784
	s_mov_b32 s10, s39
	s_add_i32 s10, s10, s16
	s_ashr_i32 s11, s10, 31
	s_lshr_b32 s11, s11, 28
	s_add_i32 s11, s10, s11
	s_and_b32 s11, s11, 0x3fffff0
	s_sub_i32 s11, s10, s11
	s_mov_b32 s10, s39
	s_add_i32 s10, s10, s16
	s_ashr_i32 s15, s10, 31
	s_lshr_b32 s15, s15, 28
	s_add_i32 s10, s10, s15
	s_lshl_b32 s10, s10, 2
	s_andn2_b32 s10, s10, 63
	v_lshl_add_u32 v0, s11, 6, v24
	v_mov_b64_e32 v[2:3], s[8:9]
	s_ashr_i32 s11, s10, 31
	v_mad_i64_i32 v[12:13], s[18:19], v0, s69, v[2:3]
	s_lshl_b64 s[10:11], s[10:11], 2
	v_add_u32_e32 v0, 32, v0
	v_lshl_add_u64 v[12:13], v[12:13], 0, s[10:11]
	v_mov_b32_e32 v23, v1
	v_mad_i64_i32 v[2:3], s[18:19], v0, s69, v[2:3]
	v_lshl_add_u64 v[12:13], v[12:13], 0, v[22:23]
	v_lshl_add_u64 v[2:3], v[2:3], 0, s[10:11]
	v_lshl_add_u64 v[2:3], v[2:3], 0, v[22:23]
	global_load_dwordx4 v[12:15], v[12:13], off
	s_nop 0
	global_load_dwordx4 v[16:19], v[2:3], off
	s_add_u32 s10, s4, 0x1280000
	s_addc_u32 s11, s5, 0
	s_andn2_b64 vcc, exec, s[12:13]
	s_cbranch_vccz .LBB0_785
	s_branch .LBB0_795

; __device__ __forceinline__ int BID() { int t = blockIdx.x; asm volatile("" : "+s"(t)); return t; }
; __device__ __forceinline__ int NBLK() { int t = gridDim.x; asm volatile("" : "+s"(t)); return t; }
; __device__ __forceinline__ void tr_cvt(const float* __restrict__ src, const float* __restrict__ src2, int srcsel, int ld, int K, int N, bf16_t* __restrict__ dst, LAS float* tl) {
;     ...
;     const int G2 = 2 * NBLK();
;     int t = BID();
;     if (t < ntiles) TRC_LOAD(t, 0);
;     if (t + NBLK() < ntiles) TRC_LOAD(t + NBLK(), 1);
; __device__ void prep_phase(const Params& p, int l, LAS unsigned char* lds) {
;     ...
;     tr_cvt(w_in + 2080, nullptr, 0, WINC, D_, ZRC - 32, W + W_IN + (size_t)ZGC * D_, tl);
.LBB0_795:
	s_add_u32 s12, s8, 0x2080
	v_mov_b32_e32 v25, v168
	s_addc_u32 s13, s9, 0
	s_mov_b32 s16, s39
	v_lshlrev_b32_e32 v0, 2, v25
	s_mov_b32 s20, s73
	v_and_b32_e32 v20, 60, v0
	s_cmpk_lt_i32 s20, 0x1b0
	v_ashrrev_i32_e32 v24, 4, v25
	s_cselect_b64 s[14:15], -1, 0
	s_cmpk_gt_i32 s20, 0x1af
	v_lshlrev_b32_e32 v22, 2, v20
	s_cbranch_scc1 .LBB0_797
	s_ashr_i32 s17, s20, 31
	s_lshr_b32 s17, s17, 28
	s_add_i32 s17, s20, s17
	s_and_b32 s18, s17, 0x3fffff0
	s_lshl_b32 s17, s17, 2
	s_sub_i32 s19, s20, s18
	s_and_b32 s18, s17, 0xffffffc0
	v_lshl_add_u32 v0, s19, 6, v24
	v_mov_b64_e32 v[2:3], s[12:13]
	s_ashr_i32 s19, s18, 31
	v_mad_i64_i32 v[4:5], s[24:25], v0, s69, v[2:3]
	s_lshl_b64 s[18:19], s[18:19], 2
	v_add_u32_e32 v0, 32, v0
	v_lshl_add_u64 v[4:5], v[4:5], 0, s[18:19]
	v_mov_b32_e32 v23, v1
	v_mad_i64_i32 v[2:3], s[24:25], v0, s69, v[2:3]
	v_lshl_add_u64 v[4:5], v[4:5], 0, v[22:23]
	v_lshl_add_u64 v[2:3], v[2:3], 0, s[18:19]
	v_lshl_add_u64 v[2:3], v[2:3], 0, v[22:23]
	global_load_dwordx4 v[4:7], v[4:5], off
	s_nop 0
	global_load_dwordx4 v[8:11], v[2:3], off
	s_branch .LBB0_798
.LBB0_797:
	v_mov_b32_e32 v2, v1
	v_mov_b32_e32 v3, v1
	v_mov_b32_e32 v0, v1
	v_mov_b64_e32 v[6:7], v[2:3]
	v_mov_b64_e32 v[10:11], v[2:3]
	v_mov_b64_e32 v[4:5], v[0:1]
	v_mov_b64_e32 v[8:9], v[0:1]
.LBB0_798:
	s_mov_b32 s17, s39
	s_add_i32 s17, s17, s20
	s_cmpk_gt_i32 s17, 0x1af
	s_cbranch_scc1 .LBB0_800
	s_mov_b32 s17, s39
	s_add_i32 s17, s17, s20
	s_ashr_i32 s18, s17, 31
	s_lshr_b32 s18, s18, 28
	s_add_i32 s18, s17, s18
	s_and_b32 s18, s18, 0x3fffff0
	s_sub_i32 s17, s17, s18
	s_mov_b32 s18, s39
	s_add_i32 s18, s18, s20
	s_ashr_i32 s19, s18, 31
	s_lshr_b32 s19, s19, 28
	s_add_i32 s18, s18, s19
	s_lshl_b32 s18, s18, 2
	s_andn2_b32 s18, s18, 63
	v_lshl_add_u32 v0, s17, 6, v24
	v_mov_b64_e32 v[2:3], s[12:13]
	s_ashr_i32 s19, s18, 31
	v_mad_i64_i32 v[12:13], s[24:25], v0, s69, v[2:3]
	s_lshl_b64 s[18:19], s[18:19], 2
	v_add_u32_e32 v0, 32, v0
	v_lshl_add_u64 v[12:13], v[12:13], 0, s[18:19]
	v_mov_b32_e32 v23, v1
	v_mad_i64_i32 v[2:3], s[24:25], v0, s69, v[2:3]
	v_lshl_add_u64 v[12:13], v[12:13], 0, v[22:23]
	v_lshl_add_u64 v[2:3], v[2:3], 0, s[18:19]
	v_lshl_add_u64 v[2:3], v[2:3], 0, v[22:23]
	global_load_dwordx4 v[12:15], v[12:13], off
	s_nop 0
	global_load_dwordx4 v[16:19], v[2:3], off
	s_andn2_b64 vcc, exec, s[14:15]
	s_cbranch_vccz .LBB0_801
	s_branch .LBB0_811

; __device__ __forceinline__ int BID() { int t = blockIdx.x; asm volatile("" : "+s"(t)); return t; }
; __device__ __forceinline__ int NBLK() { int t = gridDim.x; asm volatile("" : "+s"(t)); return t; }
; __device__ __forceinline__ void tr_cvt(const float* __restrict__ src, const float* __restrict__ src2, int srcsel, int ld, int K, int N, bf16_t* __restrict__ dst, LAS float* tl) {
;     ...
;     const int G2 = 2 * NBLK();
;     int t = BID();
;     if (t < ntiles) TRC_LOAD(t, 0);
;     if (t + NBLK() < ntiles) TRC_LOAD(t + NBLK(), 1);
; __device__ void prep_phase(const Params& p, int l, LAS unsigned char* lds) {
;     ...
;     tr_cvt(w_in + 3840, nullptr, 0, WINC, D_, 3072, W + W_GATE, tl);
.LBB0_811:
	s_add_u32 s12, s8, 0x3c00
	v_mov_b32_e32 v25, v168
	s_addc_u32 s13, s9, 0
	s_mov_b32 s16, s39
	v_lshlrev_b32_e32 v0, 2, v25
	s_mov_b32 s20, s73
	v_and_b32_e32 v20, 60, v0
	s_cmpk_lt_i32 s20, 0x300
	v_ashrrev_i32_e32 v24, 4, v25
	s_cselect_b64 s[14:15], -1, 0
	s_cmpk_gt_i32 s20, 0x2ff
	v_lshlrev_b32_e32 v22, 2, v20
	s_cbranch_scc1 .LBB0_813
	s_ashr_i32 s17, s20, 31
	s_lshr_b32 s17, s17, 28
	s_add_i32 s17, s20, s17
	s_and_b32 s18, s17, 0x3fffff0
	s_lshl_b32 s17, s17, 2
	s_sub_i32 s19, s20, s18
	s_and_b32 s18, s17, 0xffffffc0
	v_lshl_add_u32 v0, s19, 6, v24
	v_mov_b64_e32 v[2:3], s[12:13]
	s_ashr_i32 s19, s18, 31
	v_mad_i64_i32 v[4:5], s[24:25], v0, s69, v[2:3]
	s_lshl_b64 s[18:19], s[18:19], 2
	v_add_u32_e32 v0, 32, v0
	v_lshl_add_u64 v[4:5], v[4:5], 0, s[18:19]
	v_mov_b32_e32 v23, v1
	v_mad_i64_i32 v[2:3], s[24:25], v0, s69, v[2:3]
	v_lshl_add_u64 v[4:5], v[4:5], 0, v[22:23]
	v_lshl_add_u64 v[2:3], v[2:3], 0, s[18:19]
	v_lshl_add_u64 v[2:3], v[2:3], 0, v[22:23]
	global_load_dwordx4 v[4:7], v[4:5], off
	s_nop 0
	global_load_dwordx4 v[8:11], v[2:3], off
	s_branch .LBB0_814
.LBB0_813:
	v_mov_b32_e32 v2, v1
	v_mov_b32_e32 v3, v1
	v_mov_b32_e32 v0, v1
	v_mov_b64_e32 v[6:7], v[2:3]
	v_mov_b64_e32 v[10:11], v[2:3]
	v_mov_b64_e32 v[4:5], v[0:1]
	v_mov_b64_e32 v[8:9], v[0:1]
.LBB0_814:
	s_mov_b32 s17, s39
	s_add_i32 s17, s17, s20
	s_cmpk_gt_i32 s17, 0x2ff
	s_cbranch_scc1 .LBB0_816
	s_mov_b32 s17, s39
	s_add_i32 s17, s17, s20
	s_ashr_i32 s18, s17, 31
	s_lshr_b32 s18, s18, 28
	s_add_i32 s18, s17, s18
	s_and_b32 s18, s18, 0x3fffff0
	s_sub_i32 s17, s17, s18
	s_mov_b32 s18, s39
	s_add_i32 s18, s18, s20
	s_ashr_i32 s19, s18, 31
	s_lshr_b32 s19, s19, 28
	s_add_i32 s18, s18, s19
	s_lshl_b32 s18, s18, 2
	s_andn2_b32 s18, s18, 63
	v_lshl_add_u32 v0, s17, 6, v24
	v_mov_b64_e32 v[2:3], s[12:13]
	s_ashr_i32 s19, s18, 31
	v_mad_i64_i32 v[12:13], s[24:25], v0, s69, v[2:3]
	s_lshl_b64 s[18:19], s[18:19], 2
	v_add_u32_e32 v0, 32, v0
	v_lshl_add_u64 v[12:13], v[12:13], 0, s[18:19]
	v_mov_b32_e32 v23, v1
	v_mad_i64_i32 v[2:3], s[24:25], v0, s69, v[2:3]
	v_lshl_add_u64 v[12:13], v[12:13], 0, v[22:23]
	v_lshl_add_u64 v[2:3], v[2:3], 0, s[18:19]
	v_lshl_add_u64 v[2:3], v[2:3], 0, v[22:23]
	global_load_dwordx4 v[12:15], v[12:13], off
	s_nop 0
	global_load_dwordx4 v[16:19], v[2:3], off
	s_andn2_b64 vcc, exec, s[14:15]
	s_cbranch_vccz .LBB0_817
	s_branch .LBB0_827

; __device__ __forceinline__ const float* INP(const Params& p, int i) { asm volatile("" : "+s"(i)); return p.in[i]; }
; __device__ __forceinline__ int BID() { int t = blockIdx.x; asm volatile("" : "+s"(t)); return t; }
; __device__ __forceinline__ int NBLK() { int t = gridDim.x; asm volatile("" : "+s"(t)); return t; }
; __device__ __forceinline__ void tr_cvt(const float* __restrict__ src, const float* __restrict__ src2, int srcsel, int ld, int K, int N, bf16_t* __restrict__ dst, LAS float* tl) {
;     ...
;     const int G2 = 2 * NBLK();
;     int t = BID();
;     if (t < ntiles) TRC_LOAD(t, 0);
;     if (t + NBLK() < ntiles) TRC_LOAD(t + NBLK(), 1);
; __device__ void prep_phase(const Params& p, int l, LAS unsigned char* lds) {
;     ...
;     tr_cvt(INP(p, 27) + (size_t)l * 512 * D_, nullptr, 0, D_, 512, D_, W + W_PROJ, tl);
.LBB0_827:
	s_mov_b32 s12, 27
	s_ashr_i32 s13, s12, 31
	s_lshl_b64 s[12:13], s[12:13], 3
	s_add_u32 s12, s0, s12
	s_addc_u32 s13, s1, s13
	s_load_dwordx2 s[12:13], s[12:13], 0x0
	s_lshl_b64 s[14:15], s[60:61], 21
	v_mov_b32_e32 v25, v168
	s_mov_b32 s16, s39
	s_waitcnt lgkmcnt(0)
	s_add_u32 s12, s12, s14
	s_addc_u32 s13, s13, s15
	v_lshlrev_b32_e32 v0, 2, v25
	s_mov_b32 s20, s73
	v_and_b32_e32 v20, 60, v0
	s_cmpk_lt_i32 s20, 0x80
	v_ashrrev_i32_e32 v24, 4, v25
	s_cselect_b64 s[14:15], -1, 0
	s_cmpk_gt_i32 s20, 0x7f
	v_lshlrev_b32_e32 v22, 2, v20
	s_cbranch_scc1 .LBB0_829
	s_ashr_i32 s17, s20, 31
	s_lshr_b32 s17, s17, 29
	s_add_i32 s17, s20, s17
	s_and_b32 s18, s17, 0x3fffff8
	s_sub_i32 s19, s20, s18
	v_lshl_add_u32 v2, s19, 6, v24
	s_lshl_b32 s17, s17, 3
	v_ashrrev_i32_e32 v3, 31, v2
	s_and_b32 s18, s17, 0xffffffc0
	v_lshlrev_b64 v[2:3], 12, v[2:3]
	v_lshl_add_u64 v[2:3], s[12:13], 0, v[2:3]
	s_ashr_i32 s19, s18, 31
	v_lshl_add_u64 v[2:3], s[18:19], 2, v[2:3]
	v_mov_b32_e32 v23, v1
	v_lshl_add_u64 v[2:3], v[2:3], 0, v[22:23]
	v_add_co_u32_e32 v8, vcc, 0x20000, v2
	s_nop 1
	v_addc_co_u32_e32 v9, vcc, 0, v3, vcc
	global_load_dwordx4 v[4:7], v[2:3], off
	s_nop 0
	global_load_dwordx4 v[8:11], v[8:9], off
	s_branch .LBB0_830
.LBB0_829:
	v_mov_b32_e32 v2, v1
	v_mov_b32_e32 v3, v1
	v_mov_b32_e32 v0, v1
	v_mov_b64_e32 v[6:7], v[2:3]
	v_mov_b64_e32 v[10:11], v[2:3]
	v_mov_b64_e32 v[4:5], v[0:1]
	v_mov_b64_e32 v[8:9], v[0:1]
.LBB0_830:
	s_mov_b32 s17, s39
	s_add_i32 s17, s17, s20
	s_cmpk_gt_i32 s17, 0x7f
	s_cbranch_scc1 .LBB0_832
	s_mov_b32 s17, s39
	s_add_i32 s17, s17, s20
	s_ashr_i32 s18, s17, 31
	s_lshr_b32 s18, s18, 29
	s_add_i32 s18, s17, s18
	s_and_b32 s18, s18, 0x3fffff8
	s_sub_i32 s17, s17, s18
	s_mov_b32 s18, s39
	s_add_i32 s18, s18, s20
	s_ashr_i32 s19, s18, 31
	s_lshr_b32 s19, s19, 29
	s_add_i32 s18, s18, s19
	v_lshl_add_u32 v2, s17, 6, v24
	s_lshl_b32 s18, s18, 3
	v_ashrrev_i32_e32 v3, 31, v2
	s_andn2_b32 s18, s18, 63
	v_lshlrev_b64 v[2:3], 12, v[2:3]
	v_lshl_add_u64 v[2:3], s[12:13], 0, v[2:3]
	s_ashr_i32 s19, s18, 31
	v_lshl_add_u64 v[2:3], s[18:19], 2, v[2:3]
	v_mov_b32_e32 v23, v1
	v_lshl_add_u64 v[2:3], v[2:3], 0, v[22:23]
	v_add_co_u32_e32 v16, vcc, 0x20000, v2
	s_nop 1
	v_addc_co_u32_e32 v17, vcc, 0, v3, vcc
	global_load_dwordx4 v[12:15], v[2:3], off
	s_nop 0
	global_load_dwordx4 v[16:19], v[16:17], off
	s_andn2_b64 vcc, exec, s[14:15]
	s_cbranch_vccz .LBB0_833
	s_branch .LBB0_843

; __device__ __forceinline__ const float* INP(const Params& p, int i) { asm volatile("" : "+s"(i)); return p.in[i]; }
; __device__ __forceinline__ int BID() { int t = blockIdx.x; asm volatile("" : "+s"(t)); return t; }
; __device__ __forceinline__ int NBLK() { int t = gridDim.x; asm volatile("" : "+s"(t)); return t; }
; __device__ __forceinline__ void tr_cvt(const float* __restrict__ src, const float* __restrict__ src2, int srcsel, int ld, int K, int N, bf16_t* __restrict__ dst, LAS float* tl) {
;     ...
;     const int G2 = 2 * NBLK();
;     int t = BID();
;     if (t < ntiles) TRC_LOAD(t, 0);
;     if (t + NBLK() < ntiles) TRC_LOAD(t + NBLK(), 1);
; __device__ void prep_phase(const Params& p, int l, LAS unsigned char* lds) {
;     ...
;     tr_cvt(INP(p, 28) + (size_t)l * 512 * D_, nullptr, 0, D_, 512, D_, W + W_PROJ + 1024 * 512, tl);
.LBB0_843:
	s_mov_b32 s14, 28
	s_ashr_i32 s15, s14, 31
	s_lshl_b64 s[12:13], s[60:61], 19
	s_lshl_b64 s[14:15], s[14:15], 3
	s_add_u32 s14, s0, s14
	s_addc_u32 s15, s1, s15
	s_load_dwordx2 s[14:15], s[14:15], 0x0
	s_lshl_b64 s[12:13], s[12:13], 2
	v_mov_b32_e32 v25, v168
	s_mov_b32 s18, s39
	s_waitcnt lgkmcnt(0)
	s_add_u32 s14, s14, s12
	s_addc_u32 s15, s15, s13
	v_lshlrev_b32_e32 v0, 2, v25
	s_mov_b32 s24, s73
	v_and_b32_e32 v20, 60, v0
	s_cmpk_lt_i32 s24, 0x80
	v_ashrrev_i32_e32 v24, 4, v25
	s_cselect_b64 s[16:17], -1, 0
	s_cmpk_gt_i32 s24, 0x7f
	v_lshlrev_b32_e32 v22, 2, v20
	s_cbranch_scc1 .LBB0_845
	s_ashr_i32 s19, s24, 31
	s_lshr_b32 s19, s19, 29
	s_add_i32 s19, s24, s19
	s_and_b32 s20, s19, 0x3fffff8
	s_sub_i32 s21, s24, s20
	v_lshl_add_u32 v2, s21, 6, v24
	s_lshl_b32 s19, s19, 3
	v_ashrrev_i32_e32 v3, 31, v2
	s_and_b32 s20, s19, 0xffffffc0
	v_lshlrev_b64 v[2:3], 12, v[2:3]
	v_lshl_add_u64 v[2:3], s[14:15], 0, v[2:3]
	s_ashr_i32 s21, s20, 31
	v_lshl_add_u64 v[2:3], s[20:21], 2, v[2:3]
	v_mov_b32_e32 v23, v1
	v_lshl_add_u64 v[2:3], v[2:3], 0, v[22:23]
	v_add_co_u32_e32 v8, vcc, 0x20000, v2
	s_nop 1
	v_addc_co_u32_e32 v9, vcc, 0, v3, vcc
	global_load_dwordx4 v[4:7], v[2:3], off
	s_nop 0
	global_load_dwordx4 v[8:11], v[8:9], off
	s_branch .LBB0_846
.LBB0_845:
	v_mov_b32_e32 v2, v1
	v_mov_b32_e32 v3, v1
	v_mov_b32_e32 v0, v1
	v_mov_b64_e32 v[6:7], v[2:3]
	v_mov_b64_e32 v[10:11], v[2:3]
	v_mov_b64_e32 v[4:5], v[0:1]
	v_mov_b64_e32 v[8:9], v[0:1]
.LBB0_846:
	s_mov_b32 s19, s39
	s_add_i32 s19, s19, s24
	s_cmpk_gt_i32 s19, 0x7f
	s_cbranch_scc1 .LBB0_848
	s_mov_b32 s19, s39
	s_add_i32 s19, s19, s24
	s_ashr_i32 s20, s19, 31
	s_lshr_b32 s20, s20, 29
	s_add_i32 s20, s19, s20
	s_and_b32 s20, s20, 0x3fffff8
	s_sub_i32 s19, s19, s20
	s_mov_b32 s20, s39
	s_add_i32 s20, s20, s24
	s_ashr_i32 s21, s20, 31
	s_lshr_b32 s21, s21, 29
	s_add_i32 s20, s20, s21
	v_lshl_add_u32 v2, s19, 6, v24
	s_lshl_b32 s20, s20, 3
	v_ashrrev_i32_e32 v3, 31, v2
	s_andn2_b32 s20, s20, 63
	v_lshlrev_b64 v[2:3], 12, v[2:3]
	v_lshl_add_u64 v[2:3], s[14:15], 0, v[2:3]
	s_ashr_i32 s21, s20, 31
	v_lshl_add_u64 v[2:3], s[20:21], 2, v[2:3]
	v_mov_b32_e32 v23, v1
	v_lshl_add_u64 v[2:3], v[2:3], 0, v[22:23]
	v_add_co_u32_e32 v16, vcc, 0x20000, v2
	s_nop 1
	v_addc_co_u32_e32 v17, vcc, 0, v3, vcc
	global_load_dwordx4 v[12:15], v[2:3], off
	s_nop 0
	global_load_dwordx4 v[16:19], v[16:17], off
	s_andn2_b64 vcc, exec, s[16:17]
	s_cbranch_vccz .LBB0_849
	s_branch .LBB0_859

; __device__ __forceinline__ const float* INP(const Params& p, int i) { asm volatile("" : "+s"(i)); return p.in[i]; }
; __device__ __forceinline__ int BID() { int t = blockIdx.x; asm volatile("" : "+s"(t)); return t; }
; __device__ __forceinline__ int NBLK() { int t = gridDim.x; asm volatile("" : "+s"(t)); return t; }
; __device__ __forceinline__ void tr_cvt(const float* __restrict__ src, const float* __restrict__ src2, int srcsel, int ld, int K, int N, bf16_t* __restrict__ dst, LAS float* tl) {
;     ...
;     const int G2 = 2 * NBLK();
;     int t = BID();
;     if (t < ntiles) TRC_LOAD(t, 0);
;     if (t + NBLK() < ntiles) TRC_LOAD(t + NBLK(), 1);
; __device__ void prep_phase(const Params& p, int l, LAS unsigned char* lds) {
;     ...
;     tr_cvt(INP(p, 29) + (size_t)l * 512 * D_, nullptr, 0, D_, 512, D_, W + W_PROJ + 2 * 1024 * 512, tl);
.LBB0_859:
	s_mov_b32 s14, 29
	s_ashr_i32 s15, s14, 31
	s_lshl_b64 s[14:15], s[14:15], 3
	s_add_u32 s14, s0, s14
	s_addc_u32 s15, s1, s15
	s_load_dwordx2 s[14:15], s[14:15], 0x0
	v_mov_b32_e32 v25, v168
	s_mov_b32 s16, s39
	v_lshlrev_b32_e32 v0, 2, v25
	s_waitcnt lgkmcnt(0)
	s_add_u32 s12, s14, s12
	s_addc_u32 s13, s15, s13
	s_mov_b32 s20, s73
	v_and_b32_e32 v20, 60, v0
	s_cmpk_lt_i32 s20, 0x80
	v_ashrrev_i32_e32 v24, 4, v25
	s_cselect_b64 s[14:15], -1, 0
	s_cmpk_gt_i32 s20, 0x7f
	v_lshlrev_b32_e32 v22, 2, v20
	s_cbranch_scc1 .LBB0_861
	s_ashr_i32 s17, s20, 31
	s_lshr_b32 s17, s17, 29
	s_add_i32 s17, s20, s17
	s_and_b32 s18, s17, 0x3fffff8
	s_sub_i32 s19, s20, s18
	v_lshl_add_u32 v2, s19, 6, v24
	s_lshl_b32 s17, s17, 3
	v_ashrrev_i32_e32 v3, 31, v2
	s_and_b32 s18, s17, 0xffffffc0
	v_lshlrev_b64 v[2:3], 12, v[2:3]
	v_lshl_add_u64 v[2:3], s[12:13], 0, v[2:3]
	s_ashr_i32 s19, s18, 31
	v_lshl_add_u64 v[2:3], s[18:19], 2, v[2:3]
	v_mov_b32_e32 v23, v1
	v_lshl_add_u64 v[2:3], v[2:3], 0, v[22:23]
	v_add_co_u32_e32 v8, vcc, 0x20000, v2
	s_nop 1
	v_addc_co_u32_e32 v9, vcc, 0, v3, vcc
	global_load_dwordx4 v[4:7], v[2:3], off
	s_nop 0
	global_load_dwordx4 v[8:11], v[8:9], off
	s_branch .LBB0_862
.LBB0_861:
	v_mov_b32_e32 v2, v1
	v_mov_b32_e32 v3, v1
	v_mov_b32_e32 v0, v1
	v_mov_b64_e32 v[6:7], v[2:3]
	v_mov_b64_e32 v[10:11], v[2:3]
	v_mov_b64_e32 v[4:5], v[0:1]
	v_mov_b64_e32 v[8:9], v[0:1]
.LBB0_862:
	s_mov_b32 s17, s39
	s_add_i32 s17, s17, s20
	s_cmpk_gt_i32 s17, 0x7f
	s_cbranch_scc1 .LBB0_864
	s_mov_b32 s17, s39
	s_add_i32 s17, s17, s20
	s_ashr_i32 s18, s17, 31
	s_lshr_b32 s18, s18, 29
	s_add_i32 s18, s17, s18
	s_and_b32 s18, s18, 0x3fffff8
	s_sub_i32 s17, s17, s18
	s_mov_b32 s18, s39
	s_add_i32 s18, s18, s20
	s_ashr_i32 s19, s18, 31
	s_lshr_b32 s19, s19, 29
	s_add_i32 s18, s18, s19
	v_lshl_add_u32 v2, s17, 6, v24
	s_lshl_b32 s18, s18, 3
	v_ashrrev_i32_e32 v3, 31, v2
	s_andn2_b32 s18, s18, 63
	v_lshlrev_b64 v[2:3], 12, v[2:3]
	v_lshl_add_u64 v[2:3], s[12:13], 0, v[2:3]
	s_ashr_i32 s19, s18, 31
	v_lshl_add_u64 v[2:3], s[18:19], 2, v[2:3]
	v_mov_b32_e32 v23, v1
	v_lshl_add_u64 v[2:3], v[2:3], 0, v[22:23]
	v_add_co_u32_e32 v16, vcc, 0x20000, v2
	s_nop 1
	v_addc_co_u32_e32 v17, vcc, 0, v3, vcc
	global_load_dwordx4 v[12:15], v[2:3], off
	s_nop 0
	global_load_dwordx4 v[16:19], v[16:17], off
	s_andn2_b64 vcc, exec, s[14:15]
	s_cbranch_vccz .LBB0_865
	s_branch .LBB0_875

; __device__ __forceinline__ const float* INP(const Params& p, int i) { asm volatile("" : "+s"(i)); return p.in[i]; }
; __device__ __forceinline__ int BID() { int t = blockIdx.x; asm volatile("" : "+s"(t)); return t; }
; __device__ __forceinline__ int NBLK() { int t = gridDim.x; asm volatile("" : "+s"(t)); return t; }
; __device__ __forceinline__ void tr_cvt(const float* __restrict__ src, const float* __restrict__ src2, int srcsel, int ld, int K, int N, bf16_t* __restrict__ dst, LAS float* tl) {
;     ...
;     const int G2 = 2 * NBLK();
;     int t = BID();
;     if (t < ntiles) TRC_LOAD(t, 0);
;     if (t + NBLK() < ntiles) TRC_LOAD(t + NBLK(), 1);
; __device__ void prep_phase(const Params& p, int l, LAS unsigned char* lds) {
;     ...
;     tr_cvt(INP(p, 30) + (size_t)l * D_ * D_, nullptr, 0, D_, D_, D_, W + W_OUT, tl);
.LBB0_875:
	s_mov_b32 s14, 30
	s_ashr_i32 s15, s14, 31
	s_lshl_b64 s[12:13], s[60:61], 22
	s_lshl_b64 s[14:15], s[14:15], 3
	s_add_u32 s14, s0, s14
	s_addc_u32 s15, s1, s15
	s_load_dwordx2 s[14:15], s[14:15], 0x0
	v_mov_b32_e32 v25, v168
	s_mov_b32 s16, s39
	v_lshlrev_b32_e32 v0, 2, v25
	s_waitcnt lgkmcnt(0)
	s_add_u32 s12, s14, s12
	s_addc_u32 s13, s15, s13
	s_mov_b32 s20, s73
	v_and_b32_e32 v20, 60, v0
	s_cmpk_lt_i32 s20, 0x100
	v_ashrrev_i32_e32 v24, 4, v25
	s_cselect_b64 s[14:15], -1, 0
	s_cmpk_gt_i32 s20, 0xff
	v_lshlrev_b32_e32 v22, 2, v20
	s_cbranch_scc1 .LBB0_877
	s_ashr_i32 s17, s20, 31
	s_lshr_b32 s17, s17, 28
	s_add_i32 s17, s20, s17
	s_and_b32 s18, s17, 0x3fffff0
	s_sub_i32 s19, s20, s18
	v_lshl_add_u32 v2, s19, 6, v24
	s_lshl_b32 s17, s17, 2
	v_ashrrev_i32_e32 v3, 31, v2
	s_and_b32 s18, s17, 0xffffffc0
	v_lshlrev_b64 v[2:3], 12, v[2:3]
	v_lshl_add_u64 v[2:3], s[12:13], 0, v[2:3]
	s_ashr_i32 s19, s18, 31
	v_lshl_add_u64 v[2:3], s[18:19], 2, v[2:3]
	v_mov_b32_e32 v23, v1
	v_lshl_add_u64 v[2:3], v[2:3], 0, v[22:23]
	v_add_co_u32_e32 v8, vcc, 0x20000, v2
	s_nop 1
	v_addc_co_u32_e32 v9, vcc, 0, v3, vcc
	global_load_dwordx4 v[4:7], v[2:3], off
	s_nop 0
	global_load_dwordx4 v[8:11], v[8:9], off
	s_branch .LBB0_878
.LBB0_877:
	v_mov_b32_e32 v2, v1
	v_mov_b32_e32 v3, v1
	v_mov_b32_e32 v0, v1
	v_mov_b64_e32 v[6:7], v[2:3]
	v_mov_b64_e32 v[10:11], v[2:3]
	v_mov_b64_e32 v[4:5], v[0:1]
	v_mov_b64_e32 v[8:9], v[0:1]
.LBB0_878:
	s_mov_b32 s17, s39
	s_add_i32 s17, s17, s20
	s_cmpk_gt_i32 s17, 0xff
	s_cbranch_scc1 .LBB0_880
	s_mov_b32 s17, s39
	s_add_i32 s17, s17, s20
	s_ashr_i32 s18, s17, 31
	s_lshr_b32 s18, s18, 28
	s_add_i32 s18, s17, s18
	s_and_b32 s18, s18, 0x3fffff0
	s_sub_i32 s17, s17, s18
	s_mov_b32 s18, s39
	s_add_i32 s18, s18, s20
	s_ashr_i32 s19, s18, 31
	s_lshr_b32 s19, s19, 28
	s_add_i32 s18, s18, s19
	v_lshl_add_u32 v2, s17, 6, v24
	s_lshl_b32 s18, s18, 2
	v_ashrrev_i32_e32 v3, 31, v2
	s_andn2_b32 s18, s18, 63
	v_lshlrev_b64 v[2:3], 12, v[2:3]
	v_lshl_add_u64 v[2:3], s[12:13], 0, v[2:3]
	s_ashr_i32 s19, s18, 31
	v_lshl_add_u64 v[2:3], s[18:19], 2, v[2:3]
	v_mov_b32_e32 v23, v1
	v_lshl_add_u64 v[2:3], v[2:3], 0, v[22:23]
	v_add_co_u32_e32 v16, vcc, 0x20000, v2
	s_nop 1
	v_addc_co_u32_e32 v17, vcc, 0, v3, vcc
	global_load_dwordx4 v[12:15], v[2:3], off
	s_nop 0
	global_load_dwordx4 v[16:19], v[16:17], off
	s_andn2_b64 vcc, exec, s[14:15]
	s_cbranch_vccz .LBB0_881
	s_branch .LBB0_891

; __device__ __forceinline__ const float* INP(const Params& p, int i) { asm volatile("" : "+s"(i)); return p.in[i]; }
; __device__ __forceinline__ int BID() { int t = blockIdx.x; asm volatile("" : "+s"(t)); return t; }
; __device__ __forceinline__ int NBLK() { int t = gridDim.x; asm volatile("" : "+s"(t)); return t; }
; __device__ __forceinline__ void tr_cvt(const float* __restrict__ src, const float* __restrict__ src2, int srcsel, int ld, int K, int N, bf16_t* __restrict__ dst, LAS float* tl) {
;     ...
;     const int G2 = 2 * NBLK();
;     int t = BID();
;     if (t < ntiles) TRC_LOAD(t, 0);
;     if (t + NBLK() < ntiles) TRC_LOAD(t + NBLK(), 1);
; __device__ void prep_phase(const Params& p, int l, LAS unsigned char* lds) {
;     ...
;     tr_cvt(INP(p, 32) + (size_t)l * D_ * FF_, INP(p, 33) + (size_t)l * D_ * FF_, 1, FF_, D_, 5632, W + W_GU2, tl);
.LBB0_891:
	s_mov_b32 s12, 32
	s_ashr_i32 s13, s12, 31
	s_lshl_b64 s[12:13], s[12:13], 3
	s_add_u32 s12, s0, s12
	s_addc_u32 s13, s1, s13
	s_load_dwordx2 s[12:13], s[12:13], 0x0
	s_mov_b32 s14, 33
	v_mov_b32_e32 v25, v168
	s_mov_b32 s24, s73
	s_waitcnt lgkmcnt(0)
	s_add_u32 s18, s12, s6
	s_addc_u32 s19, s13, s7
	s_ashr_i32 s15, s14, 31
	s_lshl_b64 s[12:13], s[14:15], 3
	s_add_u32 s12, s0, s12
	s_addc_u32 s13, s1, s13
	s_load_dwordx2 s[12:13], s[12:13], 0x0
	s_mov_b32 s14, s39
	v_lshlrev_b32_e32 v0, 2, v25
	v_and_b32_e32 v20, 60, v0
	s_waitcnt lgkmcnt(0)
	s_add_u32 s20, s12, s6
	s_addc_u32 s21, s13, s7
	s_cmpk_lt_i32 s24, 0x580
	v_ashrrev_i32_e32 v24, 4, v25
	s_cselect_b64 s[12:13], -1, 0
	s_cmpk_gt_i32 s24, 0x57f
	v_lshlrev_b32_e32 v22, 2, v20
	s_cbranch_scc1 .LBB0_893
	s_ashr_i32 s15, s24, 31
	s_lshr_b32 s15, s15, 28
	s_add_i32 s15, s24, s15
	s_ashr_i32 s16, s15, 4
	s_lshl_b32 s17, s16, 6
	s_and_b32 s25, s16, 2
	s_lshl_b32 s16, s16, 5
	s_and_b32 s15, s15, 0x3fffff0
	s_and_b32 s16, s16, 0xffffff80
	s_and_b32 s17, s17, 64
	s_sub_i32 s15, s24, s15
	s_or_b32 s16, s16, s17
	s_cmp_eq_u32 s25, 0
	s_cselect_b32 s35, s19, s21
	s_cselect_b32 s34, s18, s20
	v_lshl_add_u32 v0, s15, 6, v24
	v_mov_b64_e32 v[2:3], s[34:35]
	s_movk_i32 s15, 0x2c00
	s_ashr_i32 s17, s16, 31
	v_mad_i64_i32 v[4:5], s[34:35], v0, s15, v[2:3]
	s_lshl_b64 s[16:17], s[16:17], 2
	v_add_u32_e32 v0, 32, v0
	v_lshl_add_u64 v[4:5], v[4:5], 0, s[16:17]
	v_mov_b32_e32 v23, v1
	v_mad_i64_i32 v[2:3], s[34:35], v0, s15, v[2:3]
	v_lshl_add_u64 v[4:5], v[4:5], 0, v[22:23]
	v_lshl_add_u64 v[2:3], v[2:3], 0, s[16:17]
	v_lshl_add_u64 v[2:3], v[2:3], 0, v[22:23]
	global_load_dwordx4 v[4:7], v[4:5], off
	s_nop 0
	global_load_dwordx4 v[8:11], v[2:3], off
	s_branch .LBB0_894
.LBB0_893:
	v_mov_b32_e32 v2, v1
	v_mov_b32_e32 v3, v1
	v_mov_b32_e32 v0, v1
	v_mov_b64_e32 v[6:7], v[2:3]
	v_mov_b64_e32 v[10:11], v[2:3]
	v_mov_b64_e32 v[4:5], v[0:1]
	v_mov_b64_e32 v[8:9], v[0:1]
.LBB0_894:
	s_mov_b32 s15, s39
	s_add_i32 s15, s15, s24
	s_cmpk_gt_i32 s15, 0x57f
	s_cbranch_scc1 .LBB0_896
	s_mov_b32 s15, s39
	s_add_i32 s15, s15, s24
	s_ashr_i32 s16, s15, 31
	s_lshr_b32 s16, s16, 28
	s_add_i32 s16, s15, s16
	s_and_b32 s16, s16, 0x3fffff0
	s_sub_i32 s15, s15, s16
	s_mov_b32 s16, s39
	s_add_i32 s16, s16, s24
	s_ashr_i32 s17, s16, 31
	s_lshr_b32 s17, s17, 28
	s_add_i32 s16, s16, s17
	s_ashr_i32 s16, s16, 4
	s_lshl_b32 s17, s16, 6
	s_and_b32 s25, s16, 2
	s_lshl_b32 s16, s16, 5
	s_and_b32 s16, s16, 0xffffff80
	s_and_b32 s17, s17, 64
	s_or_b32 s16, s16, s17
	s_cmp_eq_u32 s25, 0
	s_cselect_b32 s35, s19, s21
	s_cselect_b32 s34, s18, s20
	v_lshl_add_u32 v0, s15, 6, v24
	v_mov_b64_e32 v[2:3], s[34:35]
	s_movk_i32 s15, 0x2c00
	s_ashr_i32 s17, s16, 31
	v_mad_i64_i32 v[12:13], s[34:35], v0, s15, v[2:3]
	s_lshl_b64 s[16:17], s[16:17], 2
	v_add_u32_e32 v0, 32, v0
	v_lshl_add_u64 v[12:13], v[12:13], 0, s[16:17]
	v_mov_b32_e32 v23, v1
	v_mad_i64_i32 v[2:3], s[34:35], v0, s15, v[2:3]
	v_lshl_add_u64 v[12:13], v[12:13], 0, v[22:23]
	v_lshl_add_u64 v[2:3], v[2:3], 0, s[16:17]
	v_lshl_add_u64 v[2:3], v[2:3], 0, v[22:23]
	global_load_dwordx4 v[12:15], v[12:13], off
	s_nop 0
	global_load_dwordx4 v[16:19], v[2:3], off
	s_andn2_b64 vcc, exec, s[12:13]
	s_cbranch_vccz .LBB0_897
	s_branch .LBB0_907

; __device__ __forceinline__ const float* INP(const Params& p, int i) { asm volatile("" : "+s"(i)); return p.in[i]; }
; __device__ __forceinline__ int BID() { int t = blockIdx.x; asm volatile("" : "+s"(t)); return t; }
; __device__ __forceinline__ int NBLK() { int t = gridDim.x; asm volatile("" : "+s"(t)); return t; }
; __device__ __forceinline__ void tr_cvt(const float* __restrict__ src, const float* __restrict__ src2, int srcsel, int ld, int K, int N, bf16_t* __restrict__ dst, LAS float* tl) {
;     ...
;     const int G2 = 2 * NBLK();
;     int t = BID();
;     if (t < ntiles) TRC_LOAD(t, 0);
;     if (t + NBLK() < ntiles) TRC_LOAD(t + NBLK(), 1);
; __device__ void prep_phase(const Params& p, int l, LAS unsigned char* lds) {
;     ...
;     tr_cvt(INP(p, 34) + (size_t)l * FF_ * D_, nullptr, 0, D_, FF_, D_, W + W_D2, tl);
.LBB0_907:
	s_mov_b32 s12, 34
	s_ashr_i32 s13, s12, 31
	s_lshl_b64 s[12:13], s[12:13], 3
	s_add_u32 s12, s0, s12
	s_addc_u32 s13, s1, s13
	s_load_dwordx2 s[12:13], s[12:13], 0x0
	v_mov_b32_e32 v25, v168
	s_mov_b32 s14, s39
	v_lshlrev_b32_e32 v0, 2, v25
	s_waitcnt lgkmcnt(0)
	s_add_u32 s6, s12, s6
	s_addc_u32 s7, s13, s7
	s_mov_b32 s16, s73
	v_and_b32_e32 v20, 60, v0
	s_cmpk_lt_i32 s16, 0x2c0
	v_ashrrev_i32_e32 v24, 4, v25
	s_cselect_b64 s[12:13], -1, 0
	s_cmpk_gt_i32 s16, 0x2bf
	v_lshlrev_b32_e32 v22, 2, v20
	s_cbranch_scc1 .LBB0_909
	s_mul_hi_i32 s15, s16, 0x2e8ba2e9
	s_lshr_b32 s17, s15, 31
	s_ashr_i32 s15, s15, 3
	s_add_i32 s15, s15, s17
	s_mul_i32 s17, s15, 44
	s_sub_i32 s17, s16, s17
	v_lshl_add_u32 v2, s17, 6, v24
	v_ashrrev_i32_e32 v3, 31, v2
	s_lshl_b32 s18, s15, 6
	v_lshlrev_b64 v[2:3], 12, v[2:3]
	v_lshl_add_u64 v[2:3], s[6:7], 0, v[2:3]
	s_ashr_i32 s19, s18, 31
	v_lshl_add_u64 v[2:3], s[18:19], 2, v[2:3]
	v_mov_b32_e32 v23, v1
	v_lshl_add_u64 v[2:3], v[2:3], 0, v[22:23]
	v_add_co_u32_e32 v8, vcc, 0x20000, v2
	s_nop 1
	v_addc_co_u32_e32 v9, vcc, 0, v3, vcc
	global_load_dwordx4 v[4:7], v[2:3], off
	s_nop 0
	global_load_dwordx4 v[8:11], v[8:9], off
	s_branch .LBB0_910
.LBB0_909:
	v_mov_b32_e32 v2, v1
	v_mov_b32_e32 v3, v1
	v_mov_b32_e32 v0, v1
	v_mov_b64_e32 v[6:7], v[2:3]
	v_mov_b64_e32 v[10:11], v[2:3]
	v_mov_b64_e32 v[4:5], v[0:1]
	v_mov_b64_e32 v[8:9], v[0:1]
.LBB0_910:
	s_mov_b32 s15, s39
	s_add_i32 s15, s15, s16
	s_cmpk_gt_i32 s15, 0x2bf
	s_cbranch_scc1 .LBB0_912
	s_mov_b32 s15, s39
	s_add_i32 s15, s15, s16
	s_mul_hi_i32 s17, s15, 0x2e8ba2e9
	s_lshr_b32 s18, s17, 31
	s_lshr_b32 s17, s17, 3
	s_add_i32 s17, s17, s18
	s_mul_i32 s17, s17, 44
	s_sub_i32 s15, s15, s17
	s_mov_b32 s17, s39
	s_add_i32 s17, s17, s16
	s_mul_hi_i32 s17, s17, 0x2e8ba2e9
	s_lshr_b32 s18, s17, 31
	s_lshr_b32 s17, s17, 3
	v_lshl_add_u32 v2, s15, 6, v24
	s_add_i32 s17, s17, s18
	v_ashrrev_i32_e32 v3, 31, v2
	s_lshl_b32 s18, s17, 6
	v_lshlrev_b64 v[2:3], 12, v[2:3]
	v_lshl_add_u64 v[2:3], s[6:7], 0, v[2:3]
	s_ashr_i32 s19, s18, 31
	v_lshl_add_u64 v[2:3], s[18:19], 2, v[2:3]
	v_mov_b32_e32 v23, v1
	v_lshl_add_u64 v[2:3], v[2:3], 0, v[22:23]
	v_add_co_u32_e32 v16, vcc, 0x20000, v2
	s_nop 1
	v_addc_co_u32_e32 v17, vcc, 0, v3, vcc
	global_load_dwordx4 v[12:15], v[2:3], off
	s_nop 0
	global_load_dwordx4 v[16:19], v[16:17], off
	s_andn2_b64 vcc, exec, s[12:13]
	s_cbranch_vccz .LBB0_913
	s_branch .LBB0_923
